# HW wave-slot stagger also at the entry of the compiled merge and ple GEMM phases (plus the four custom GEMM phases)
# baseline (speedup 1.0000x reference)
.LBB0_2029:
	s_getreg_b32 s4, hwreg(HW_REG_HW_ID, 0, 4)
	s_and_b32 s4, s4, 1
	s_cmp_eq_u32 s4, 0
	s_cbranch_scc1 .Lmg_nostag
	s_sleep 41

.LBB0_2540:
	s_getreg_b32 s21, hwreg(HW_REG_HW_ID, 0, 4)
	s_and_b32 s21, s21, 1
	s_cmp_eq_u32 s21, 0
	s_cbranch_scc1 .Lpl_nostag
	s_sleep 41
